# attention unit epilogue: sub-norm gamma loads issued before the exchange barrier by the active wave half only
# speedup vs baseline: 1.0046x; 1.0013x over previous
; __device__ __forceinline__ unsigned f2bf(float f) { unsigned u = __builtin_bit_cast(unsigned, f); return (u + 0x7fffu + ((u >> 16) & 1u)) >> 16; }
; template <bool SAMPLE> __device__ __forceinline__ void attn_unit16(const Ctx& c, LAS unsigned char* lds, int b, int h, int qb, int wave_s) {
;     ...
;     __syncthreads();
;     if (active && !mp) {
;         bf16* Y = (bf16*)(ws + WS_YD);
;         float sg[8];
; #pragma unroll
;         for (int et = 0; et < 8; ++et) sg[et] = c.subg[16 * et + c16b] * 0.8f;
; #pragma unroll
;         for (int qt = 0; qt < (SAMPLE ? 1 : 2); ++qt)
; #pragma unroll
;             for (int i = 0; i < 4; ++i) {
;                 float ss = 0.f;
; #pragma unroll
;                 for (int et = 0; et < 8; ++et) { o[qt][et][i] -= X[(g * 64 + qt * 32 + et * 4 + i) * 64 + lane2]; ss += o[qt][et][i] * o[qt][et][i]; }
;                 ss += __shfl_xor(ss, 1); ss += __shfl_xor(ss, 2); ss += __shfl_xor(ss, 4); ss += __shfl_xor(ss, 8);
;                 const float rstd = 1.f / sqrtf(ss * (1.f / 128.f) + 1e-5f);
;                 const int ql = 16 * qt + 4 * q4b + i;
;                 const size_t row = SAMPLE ? (size_t)ROW_S0 + b * 16 + ql : (size_t)b * SEQ + tq0 + ql;
; #pragma unroll
;                 for (int et = 0; et < 8; ++et) Y[row * D + h * 128 + 16 * et + c16b] = (bf16)f2bf(o[qt][et][i] * rstd * sg[et]);
.LBB0_886:
	s_andn2_b64 vcc, exec, s[2:3]
	s_mov_b64 exec, s[2:3]
	v_and_b32_e32 v49, 15, v7
	v_lshlrev_b32_e32 v10, 2, v49
	global_load_dword v50, v10, s[26:27]
	global_load_dword v51, v10, s[26:27] offset:64
	global_load_dword v53, v10, s[26:27] offset:128
	global_load_dword v65, v10, s[26:27] offset:192
	global_load_dword v71, v10, s[26:27] offset:256
	global_load_dword v83, v10, s[26:27] offset:320
	global_load_dword v100, v10, s[26:27] offset:384
	global_load_dword v101, v10, s[26:27] offset:448
	s_mov_b64 exec, -1
	s_waitcnt lgkmcnt(0)
	s_barrier
	s_cbranch_vccnz .LBB0_888
	s_lshl_b32 s0, s63, 14
	v_and_b32_e32 v49, 15, v7
	s_add_i32 s0, s0, 0
	v_lshlrev_b32_e32 v10, 2, v49
	v_lshl_add_u32 v64, v6, 2, s0
	ds_read2st64_b32 v[6:7], v64 offset1:1
	ds_read2st64_b32 v[8:9], v64 offset0:4 offset1:5
	ds_read2st64_b32 v[10:11], v64 offset0:6 offset1:7
	ds_read2st64_b32 v[12:13], v64 offset0:2 offset1:3
	ds_read2st64_b32 v[66:67], v64 offset0:8 offset1:9
	s_waitcnt lgkmcnt(4)
	v_sub_f32_e32 v6, v14, v6
	s_waitcnt lgkmcnt(3)
	v_sub_f32_e32 v8, v15, v8
	ds_read2st64_b32 v[76:77], v64 offset0:12 offset1:13
	ds_read2st64_b32 v[14:15], v64 offset0:14 offset1:15
	ds_read2st64_b32 v[16:17], v64 offset0:10 offset1:11
	ds_read2st64_b32 v[78:79], v64 offset0:16 offset1:17
	v_mul_f32_e32 v54, v8, v8
	s_waitcnt lgkmcnt(4)
	v_sub_f32_e32 v66, v19, v66
	s_waitcnt lgkmcnt(3)
	v_sub_f32_e32 v76, v18, v76
	ds_read2st64_b32 v[90:91], v64 offset0:20 offset1:21
	ds_read2st64_b32 v[18:19], v64 offset0:22 offset1:23
	ds_read2st64_b32 v[20:21], v64 offset0:18 offset1:19
	ds_read2st64_b32 v[96:97], v64 offset0:24 offset1:25
	v_fmac_f32_e32 v54, v6, v6
	v_fmac_f32_e32 v54, v66, v66
	v_fmac_f32_e32 v54, v76, v76
	s_waitcnt lgkmcnt(4)
	v_sub_f32_e32 v78, v5, v78
	ds_read2st64_b32 v[98:99], v64 offset0:28 offset1:29
	ds_read2st64_b32 v[22:23], v64 offset0:30 offset1:31
	ds_read2st64_b32 v[24:25], v64 offset0:26 offset1:27
	v_fmac_f32_e32 v54, v78, v78
	s_waitcnt lgkmcnt(6)
	v_sub_f32_e32 v90, v3, v90
	v_fmac_f32_e32 v54, v90, v90
	s_waitcnt lgkmcnt(3)
	v_sub_f32_e32 v96, v2, v96
	v_fmac_f32_e32 v54, v96, v96
	s_waitcnt lgkmcnt(2)
	v_sub_f32_e32 v98, v0, v98
	v_fmac_f32_e32 v54, v98, v98
	v_or_b32_e32 v4, s62, v4
	v_sub_f32_e32 v9, v114, v9
	v_sub_f32_e32 v67, v112, v67
	v_sub_f32_e32 v10, v92, v10
	s_waitcnt lgkmcnt(0)
	s_nop 1
	v_add_f32_dpp v0, v54, v54 quad_perm:[1,0,3,2] row_mask:0xf bank_mask:0xf
	v_sub_f32_e32 v12, v89, v12
	v_sub_f32_e32 v16, v88, v16
	v_sub_f32_e32 v14, v87, v14
	v_sub_f32_e32 v20, v86, v20
	s_waitcnt lgkmcnt(0)
	s_nop 1
	v_add_f32_dpp v0, v0, v0 quad_perm:[2,3,0,1] row_mask:0xf bank_mask:0xf
	v_sub_f32_e32 v18, v85, v18
	v_sub_f32_e32 v24, v84, v24
	v_sub_f32_e32 v22, v82, v22
	v_sub_f32_e32 v11, v81, v11
	s_waitcnt lgkmcnt(0)
	s_nop 1
	v_add_f32_dpp v0, v0, v0 row_half_mirror row_mask:0xf bank_mask:0xf
	v_sub_f32_e32 v15, v74, v15
	s_waitcnt lgkmcnt(0)
	s_nop 1
	v_add_f32_dpp v0, v0, v0 row_mirror row_mask:0xf bank_mask:0xf
	v_fmamk_f32 v0, v0, 0x3c000000, v205
	v_mul_f32_e32 v2, 0x4f800000, v0
	v_cmp_gt_f32_e32 vcc, s75, v0
	s_nop 1
	v_cndmask_b32_e32 v5, v0, v2, vcc
	v_sqrt_f32_e32 v54, v5
	v_lshlrev_b32_e32 v0, 1, v49
	v_lshl_add_u64 v[2:3], s[40:41], 0, v[0:1]
	v_add_u32_e32 v0, -1, v54
	v_add_u32_e32 v49, 1, v54
	v_fma_f32 v55, -v0, v54, v5
	v_fma_f32 v62, -v49, v54, v5
	v_cmp_ge_f32_e64 s[0:1], 0, v55
	s_waitcnt vmcnt(6)
	v_mul_f32_e32 v55, 0x3f4ccccd, v51
	v_cndmask_b32_e64 v0, v54, v0, s[0:1]
	v_cmp_lt_f32_e64 s[0:1], 0, v62
	s_waitcnt vmcnt(5)
	v_mul_f32_e32 v54, 0x3f4ccccd, v53
	s_waitcnt vmcnt(4)
	v_mul_f32_e32 v53, 0x3f4ccccd, v65
	v_cndmask_b32_e64 v0, v0, v49, s[0:1]
	v_mul_f32_e32 v49, 0x37800000, v0
	v_cndmask_b32_e32 v0, v0, v49, vcc
	v_cmp_class_f32_e32 vcc, v5, v206
	s_waitcnt vmcnt(3)
	v_mul_f32_e32 v51, 0x3f4ccccd, v71
	v_mul_f32_e32 v62, 0x3f4ccccd, v50
	v_cndmask_b32_e32 v5, v0, v5, vcc
	v_div_scale_f32 v102, s[0:1], v5, v5, 1.0
	v_rcp_f32_e32 v103, v102
	s_waitcnt vmcnt(2)
	v_mul_f32_e32 v50, 0x3f4ccccd, v83
	s_waitcnt vmcnt(1)
	v_mul_f32_e32 v49, 0x3f4ccccd, v100
	s_waitcnt vmcnt(0)
	v_mul_f32_e32 v0, 0x3f4ccccd, v101
	v_fma_f32 v65, -v102, v103, 1.0
	v_fmac_f32_e32 v103, v65, v103
	v_div_scale_f32 v65, vcc, 1.0, v5, 1.0
	v_mul_f32_e32 v71, v65, v103
	v_fma_f32 v83, -v102, v71, v65
	v_fmac_f32_e32 v71, v83, v103
	v_fma_f32 v65, -v102, v71, v65
	v_div_fmas_f32 v65, v65, v103, v71
	v_div_fixup_f32 v65, v65, v5, 1.0
	v_mul_f32_e32 v6, v6, v65
	v_mov_b32_e32 v5, s17
	v_mul_f32_e32 v6, v62, v6
	v_lshlrev_b64 v[100:101], 11, v[4:5]
	v_bfe_u32 v71, v6, 16, 1
	v_lshl_add_u64 v[100:101], v[2:3], 0, v[100:101]
	v_add3_u32 v6, v6, v71, s76
	global_store_short_d16_hi v[100:101], v6, off
	v_mul_f32_e32 v6, v8, v65
	v_mul_f32_e32 v6, v55, v6
	v_bfe_u32 v8, v6, 16, 1
	v_add3_u32 v6, v6, v8, s76
	global_store_short_d16_hi v[100:101], v6, off offset:32
	v_mul_f32_e32 v6, v66, v65
	v_mul_f32_e32 v6, v54, v6
	v_sub_f32_e32 v66, v113, v7
	v_mul_f32_e32 v7, v9, v9
	v_bfe_u32 v8, v6, 16, 1
	v_fmac_f32_e32 v7, v66, v66
	v_add3_u32 v6, v6, v8, s76
	v_fmac_f32_e32 v7, v67, v67
	v_sub_f32_e32 v71, v105, v77
	global_store_short_d16_hi v[100:101], v6, off offset:64
	v_mul_f32_e32 v6, v76, v65
	v_fmac_f32_e32 v7, v71, v71
	v_sub_f32_e32 v76, v104, v79
	v_fmac_f32_e32 v7, v76, v76
	v_sub_f32_e32 v77, v95, v91
	v_fmac_f32_e32 v7, v77, v77
	v_sub_f32_e32 v79, v94, v97
	v_fmac_f32_e32 v7, v79, v79
	v_sub_f32_e32 v83, v93, v99
	v_fmac_f32_e32 v7, v83, v83
	ds_bpermute_b32 v91, v210, v7
	v_mul_f32_e32 v6, v53, v6
	v_bfe_u32 v8, v6, 16, 1
	v_add3_u32 v6, v6, v8, s76
	global_store_short_d16_hi v[100:101], v6, off offset:96
	s_waitcnt lgkmcnt(0)
; __device__ __forceinline__ unsigned f2bf(float f) { unsigned u = __builtin_bit_cast(unsigned, f); return (u + 0x7fffu + ((u >> 16) & 1u)) >> 16; }
; template <bool SAMPLE> __device__ __forceinline__ void attn_unit16(const Ctx& c, LAS unsigned char* lds, int b, int h, int qb, int wave_s) {
;     ...
;             for (int i = 0; i < 4; ++i) {
;                 float ss = 0.f;
; #pragma unroll
;                 for (int et = 0; et < 8; ++et) { o[qt][et][i] -= X[(g * 64 + qt * 32 + et * 4 + i) * 64 + lane2]; ss += o[qt][et][i] * o[qt][et][i]; }
;                 ss += __shfl_xor(ss, 1); ss += __shfl_xor(ss, 2); ss += __shfl_xor(ss, 4); ss += __shfl_xor(ss, 8);
;                 const float rstd = 1.f / sqrtf(ss * (1.f / 128.f) + 1e-5f);
;                 const int ql = 16 * qt + 4 * q4b + i;
;                 const size_t row = SAMPLE ? (size_t)ROW_S0 + b * 16 + ql : (size_t)b * SEQ + tq0 + ql;
; #pragma unroll
;                 for (int et = 0; et < 8; ++et) Y[row * D + h * 128 + 16 * et + c16b] = (bf16)f2bf(o[qt][et][i] * rstd * sg[et]);
;             }
	v_add_f32_e32 v7, v7, v91
	v_mul_f32_e32 v6, v78, v65
	v_mul_f32_e32 v6, v51, v6
	v_bfe_u32 v78, v6, 16, 1
	v_add3_u32 v6, v6, v78, s76
	s_waitcnt lgkmcnt(0)
	s_nop 1
	v_add_f32_dpp v7, v7, v7 quad_perm:[2,3,0,1] row_mask:0xf bank_mask:0xf
	global_store_short_d16_hi v[100:101], v6, off offset:128
	v_mul_f32_e32 v6, v90, v65
	v_mul_f32_e32 v6, v50, v6
	v_bfe_u32 v78, v6, 16, 1
	v_add3_u32 v6, v6, v78, s76
	global_store_short_d16_hi v[100:101], v6, off offset:160
	s_waitcnt lgkmcnt(0)
	s_nop 1
	v_add_f32_dpp v6, v7, v7 row_half_mirror row_mask:0xf bank_mask:0xf
	v_mul_f32_e32 v8, v96, v65
	v_mul_f32_e32 v8, v49, v8
	v_bfe_u32 v78, v8, 16, 1
	v_add3_u32 v8, v8, v78, s76
	s_waitcnt lgkmcnt(0)
	s_nop 1
	v_add_f32_dpp v6, v6, v6 row_mirror row_mask:0xf bank_mask:0xf
	v_fmamk_f32 v6, v6, 0x3c000000, v205
	v_mul_f32_e32 v7, 0x4f800000, v6
	v_cmp_gt_f32_e32 vcc, s75, v6
	global_store_short_d16_hi v[100:101], v8, off offset:192
	v_mul_f32_e32 v8, v98, v65
	v_cndmask_b32_e32 v6, v6, v7, vcc
	v_sqrt_f32_e32 v7, v6
	v_mul_f32_e32 v8, v0, v8
	v_add_u32_e32 v65, -1, v7
	v_fma_f32 v78, -v65, v7, v6
	v_cmp_ge_f32_e64 s[0:1], 0, v78
	v_add_u32_e32 v78, 1, v7
	s_nop 0
	v_cndmask_b32_e64 v65, v7, v65, s[0:1]
	v_fma_f32 v7, -v78, v7, v6
	v_cmp_lt_f32_e64 s[0:1], 0, v7
	s_nop 1
	v_cndmask_b32_e64 v7, v65, v78, s[0:1]
	v_mul_f32_e32 v65, 0x37800000, v7
	v_cndmask_b32_e32 v7, v7, v65, vcc
	v_cmp_class_f32_e32 vcc, v6, v206
	v_bfe_u32 v78, v8, 16, 1
	v_add3_u32 v8, v8, v78, s76
	v_cndmask_b32_e32 v6, v7, v6, vcc
	v_div_scale_f32 v7, s[0:1], v6, v6, 1.0
	v_rcp_f32_e32 v65, v7
	global_store_short_d16_hi v[100:101], v8, off offset:224
	v_fma_f32 v8, -v7, v65, 1.0
	v_fmac_f32_e32 v65, v8, v65
	v_div_scale_f32 v8, vcc, 1.0, v6, 1.0
	v_mul_f32_e32 v78, v8, v65
	v_fma_f32 v90, -v7, v78, v8
	v_fmac_f32_e32 v78, v90, v65
	v_fma_f32 v7, -v7, v78, v8
	v_div_fmas_f32 v7, v7, v65, v78
	v_div_fixup_f32 v8, v7, v6, 1.0
	v_mul_f32_e32 v65, v66, v8
	v_mul_f32_e32 v65, v62, v65
	v_bfe_u32 v66, v65, 16, 1
	v_add3_u32 v65, v65, v66, s76
	v_mul_f32_e32 v66, v10, v10
	v_or_b32_e32 v6, 1, v4
	v_mov_b32_e32 v7, s17
	v_fmac_f32_e32 v66, v12, v12
	v_lshlrev_b64 v[6:7], 11, v[6:7]
	v_mul_f32_e32 v9, v9, v8
	v_fmac_f32_e32 v66, v16, v16
	v_lshl_add_u64 v[6:7], v[2:3], 0, v[6:7]
	v_mul_f32_e32 v9, v55, v9
	v_fmac_f32_e32 v66, v14, v14
	global_store_short_d16_hi v[6:7], v65, off
	v_bfe_u32 v65, v9, 16, 1
	v_fmac_f32_e32 v66, v20, v20
	v_add3_u32 v9, v9, v65, s76
	v_fmac_f32_e32 v66, v18, v18
	global_store_short_d16_hi v[6:7], v9, off offset:32
	v_mul_f32_e32 v9, v67, v8
	v_fmac_f32_e32 v66, v24, v24
	v_mul_f32_e32 v9, v54, v9
	v_fmac_f32_e32 v66, v22, v22
	v_bfe_u32 v65, v9, 16, 1
	v_add3_u32 v9, v9, v65, s76
	global_store_short_d16_hi v[6:7], v9, off offset:64
	v_mul_f32_e32 v9, v71, v8
	v_mul_f32_e32 v9, v53, v9
	v_bfe_u32 v65, v9, 16, 1
	v_add3_u32 v9, v9, v65, s76
	s_waitcnt lgkmcnt(0)
	s_nop 1
	v_add_f32_dpp v65, v66, v66 quad_perm:[1,0,3,2] row_mask:0xf bank_mask:0xf
	global_store_short_d16_hi v[6:7], v9, off offset:96
	v_mul_f32_e32 v9, v76, v8
	v_mul_f32_e32 v9, v51, v9
	v_bfe_u32 v67, v9, 16, 1
	s_waitcnt lgkmcnt(0)
	s_nop 1
	v_add_f32_dpp v65, v65, v65 quad_perm:[2,3,0,1] row_mask:0xf bank_mask:0xf
	v_add3_u32 v9, v9, v67, s76
	global_store_short_d16_hi v[6:7], v9, off offset:128
	v_mul_f32_e32 v9, v77, v8
	v_mul_f32_e32 v9, v50, v9
	v_bfe_u32 v67, v9, 16, 1
	v_add3_u32 v9, v9, v67, s76
	global_store_short_d16_hi v[6:7], v9, off offset:160
	s_waitcnt lgkmcnt(0)
	s_nop 1
	v_add_f32_dpp v9, v65, v65 row_half_mirror row_mask:0xf bank_mask:0xf
	v_mul_f32_e32 v66, v79, v8
	v_mul_f32_e32 v66, v49, v66
	v_bfe_u32 v67, v66, 16, 1
	v_add3_u32 v66, v66, v67, s76
	s_waitcnt lgkmcnt(0)
	s_nop 1
	v_add_f32_dpp v9, v9, v9 row_mirror row_mask:0xf bank_mask:0xf
	v_fmamk_f32 v9, v9, 0x3c000000, v205
	v_mul_f32_e32 v65, 0x4f800000, v9
	v_cmp_gt_f32_e32 vcc, s75, v9
	global_store_short_d16_hi v[6:7], v66, off offset:192
	v_mul_f32_e32 v8, v83, v8
	v_cndmask_b32_e32 v9, v9, v65, vcc
	v_sqrt_f32_e32 v65, v9
	v_mul_f32_e32 v8, v0, v8
	v_sub_f32_e32 v76, v72, v19
	v_sub_f32_e32 v77, v70, v25
	v_add_u32_e32 v66, -1, v65
	v_fma_f32 v67, -v66, v65, v9
	v_cmp_ge_f32_e64 s[0:1], 0, v67
	v_add_u32_e32 v67, 1, v65
	v_sub_f32_e32 v78, v69, v23
	v_cndmask_b32_e64 v66, v65, v66, s[0:1]
	v_fma_f32 v65, -v67, v65, v9
	v_cmp_lt_f32_e64 s[0:1], 0, v65
	s_nop 1
	v_cndmask_b32_e64 v65, v66, v67, s[0:1]
	v_mul_f32_e32 v66, 0x37800000, v65
	v_cndmask_b32_e32 v65, v65, v66, vcc
	v_cmp_class_f32_e32 vcc, v9, v206
	v_bfe_u32 v67, v8, 16, 1
	v_add3_u32 v8, v8, v67, s76
	v_cndmask_b32_e32 v9, v65, v9, vcc
	v_div_scale_f32 v65, s[0:1], v9, v9, 1.0
	v_rcp_f32_e32 v66, v65
	global_store_short_d16_hi v[6:7], v8, off offset:224
	v_fma_f32 v6, -v65, v66, 1.0
	v_fmac_f32_e32 v66, v6, v66
	v_div_scale_f32 v6, vcc, 1.0, v9, 1.0
	v_mul_f32_e32 v7, v6, v66
	v_fma_f32 v8, -v65, v7, v6
	v_fmac_f32_e32 v7, v8, v66
	v_fma_f32 v6, -v65, v7, v6
	v_div_fmas_f32 v6, v6, v66, v7
	v_div_fixup_f32 v8, v6, v9, 1.0
	v_mul_f32_e32 v9, v12, v8
	v_or_b32_e32 v6, 2, v4
	v_mov_b32_e32 v7, s17
	v_mul_f32_e32 v9, v62, v9
	v_lshlrev_b64 v[6:7], 11, v[6:7]
	v_bfe_u32 v12, v9, 16, 1
	v_lshl_add_u64 v[6:7], v[2:3], 0, v[6:7]
	v_add3_u32 v9, v9, v12, s76
	global_store_short_d16_hi v[6:7], v9, off
	v_mul_f32_e32 v9, v10, v8
	v_mul_f32_e32 v9, v55, v9
	v_bfe_u32 v10, v9, 16, 1
	v_add3_u32 v9, v9, v10, s76
	global_store_short_d16_hi v[6:7], v9, off offset:32
	v_mul_f32_e32 v9, v16, v8
	v_mul_f32_e32 v9, v54, v9
	v_bfe_u32 v10, v9, 16, 1
	v_add3_u32 v9, v9, v10, s76
	v_sub_f32_e32 v12, v80, v13
	v_mul_f32_e32 v13, v11, v11
	global_store_short_d16_hi v[6:7], v9, off offset:64
	v_mul_f32_e32 v9, v14, v8
	v_fmac_f32_e32 v13, v12, v12
	v_sub_f32_e32 v14, v75, v17
	v_fmac_f32_e32 v13, v14, v14
	v_fmac_f32_e32 v13, v15, v15
	v_sub_f32_e32 v65, v73, v21
	v_fmac_f32_e32 v13, v65, v65
	v_fmac_f32_e32 v13, v76, v76
	v_fmac_f32_e32 v13, v77, v77
	v_fmac_f32_e32 v13, v78, v78
	v_mul_f32_e32 v9, v53, v9
	v_bfe_u32 v10, v9, 16, 1
	v_add3_u32 v9, v9, v10, s76
	global_store_short_d16_hi v[6:7], v9, off offset:96
	s_waitcnt lgkmcnt(0)
; __device__ __forceinline__ unsigned f2bf(float f) { unsigned u = __builtin_bit_cast(unsigned, f); return (u + 0x7fffu + ((u >> 16) & 1u)) >> 16; }
; template <bool SAMPLE> __device__ __forceinline__ void attn_unit16(const Ctx& c, LAS unsigned char* lds, int b, int h, int qb, int wave_s) {
;     ...
;         for (int qt = 0; qt < (SAMPLE ? 1 : 2); ++qt)
; #pragma unroll
;             for (int i = 0; i < 4; ++i) {
;                 float ss = 0.f;
; #pragma unroll
;                 for (int et = 0; et < 8; ++et) { o[qt][et][i] -= X[(g * 64 + qt * 32 + et * 4 + i) * 64 + lane2]; ss += o[qt][et][i] * o[qt][et][i]; }
;                 ss += __shfl_xor(ss, 1); ss += __shfl_xor(ss, 2); ss += __shfl_xor(ss, 4); ss += __shfl_xor(ss, 8);
;                 const float rstd = 1.f / sqrtf(ss * (1.f / 128.f) + 1e-5f);
;                 const int ql = 16 * qt + 4 * q4b + i;
;                 const size_t row = SAMPLE ? (size_t)ROW_S0 + b * 16 + ql : (size_t)b * SEQ + tq0 + ql;
; #pragma unroll
;                 for (int et = 0; et < 8; ++et) Y[row * D + h * 128 + 16 * et + c16b] = (bf16)f2bf(o[qt][et][i] * rstd * sg[et]);
;             }
	s_nop 1
	v_add_f32_dpp v10, v13, v13 quad_perm:[1,0,3,2] row_mask:0xf bank_mask:0xf
	v_mul_f32_e32 v9, v20, v8
	v_mul_f32_e32 v9, v51, v9
	v_bfe_u32 v16, v9, 16, 1
	v_add3_u32 v9, v9, v16, s76
	s_waitcnt lgkmcnt(0)
	s_nop 1
	v_add_f32_dpp v10, v10, v10 quad_perm:[2,3,0,1] row_mask:0xf bank_mask:0xf
	global_store_short_d16_hi v[6:7], v9, off offset:128
	v_mul_f32_e32 v9, v18, v8
	v_mul_f32_e32 v9, v50, v9
	v_bfe_u32 v16, v9, 16, 1
	v_add3_u32 v9, v9, v16, s76
	global_store_short_d16_hi v[6:7], v9, off offset:160
	s_waitcnt lgkmcnt(0)
	s_nop 1
	v_add_f32_dpp v9, v10, v10 row_half_mirror row_mask:0xf bank_mask:0xf
	v_mul_f32_e32 v13, v24, v8
	v_mul_f32_e32 v13, v49, v13
	v_bfe_u32 v16, v13, 16, 1
	v_add3_u32 v13, v13, v16, s76
	s_waitcnt lgkmcnt(0)
	s_nop 1
	v_add_f32_dpp v9, v9, v9 row_mirror row_mask:0xf bank_mask:0xf
	v_fmamk_f32 v9, v9, 0x3c000000, v205
	v_mul_f32_e32 v10, 0x4f800000, v9
	v_cmp_gt_f32_e32 vcc, s75, v9
	global_store_short_d16_hi v[6:7], v13, off offset:192
	v_mul_f32_e32 v8, v22, v8
	v_cndmask_b32_e32 v9, v9, v10, vcc
	v_sqrt_f32_e32 v10, v9
	v_mul_f32_e32 v8, v0, v8
	v_add_u32_e32 v13, -1, v10
	v_fma_f32 v16, -v13, v10, v9
	v_cmp_ge_f32_e64 s[0:1], 0, v16
	v_add_u32_e32 v16, 1, v10
	s_nop 0
	v_cndmask_b32_e64 v13, v10, v13, s[0:1]
	v_fma_f32 v10, -v16, v10, v9
	v_cmp_lt_f32_e64 s[0:1], 0, v10
	s_nop 1
	v_cndmask_b32_e64 v10, v13, v16, s[0:1]
	v_mul_f32_e32 v13, 0x37800000, v10
	v_cndmask_b32_e32 v10, v10, v13, vcc
	v_cmp_class_f32_e32 vcc, v9, v206
	v_bfe_u32 v16, v8, 16, 1
	v_add3_u32 v8, v8, v16, s76
	v_cndmask_b32_e32 v9, v10, v9, vcc
	v_div_scale_f32 v10, s[0:1], v9, v9, 1.0
	v_rcp_f32_e32 v13, v10
	global_store_short_d16_hi v[6:7], v8, off offset:224
	v_fma_f32 v6, -v10, v13, 1.0
	v_fmac_f32_e32 v13, v6, v13
	v_div_scale_f32 v6, vcc, 1.0, v9, 1.0
	v_mul_f32_e32 v7, v6, v13
	v_fma_f32 v8, -v10, v7, v6
	v_fmac_f32_e32 v7, v8, v13
	v_fma_f32 v6, -v10, v7, v6
	v_div_fmas_f32 v6, v6, v13, v7
	v_div_fixup_f32 v79, v6, v9, 1.0
	v_mul_f32_e32 v8, v12, v79
	v_or_b32_e32 v6, 3, v4
	v_mov_b32_e32 v7, s17
	v_mul_f32_e32 v8, v62, v8
	v_lshlrev_b64 v[6:7], 11, v[6:7]
	v_bfe_u32 v9, v8, 16, 1
	v_lshl_add_u64 v[6:7], v[2:3], 0, v[6:7]
	v_add3_u32 v8, v8, v9, s76
	global_store_short_d16_hi v[6:7], v8, off
	v_mul_f32_e32 v8, v11, v79
	v_mul_f32_e32 v8, v55, v8
	v_bfe_u32 v9, v8, 16, 1
	v_add3_u32 v8, v8, v9, s76
	global_store_short_d16_hi v[6:7], v8, off offset:32
	v_mul_f32_e32 v8, v14, v79
	v_mul_f32_e32 v8, v54, v8
	v_bfe_u32 v9, v8, 16, 1
	v_add3_u32 v8, v8, v9, s76
	global_store_short_d16_hi v[6:7], v8, off offset:64
	v_mul_f32_e32 v8, v15, v79
	v_mul_f32_e32 v80, v53, v8
	ds_read2st64_b32 v[8:9], v64 offset0:32 offset1:33
	ds_read2st64_b32 v[10:11], v64 offset0:36 offset1:37
	ds_read2st64_b32 v[12:13], v64 offset0:38 offset1:39
	ds_read2st64_b32 v[14:15], v64 offset0:34 offset1:35
	ds_read2st64_b32 v[66:67], v64 offset0:40 offset1:41
	v_bfe_u32 v81, v80, 16, 1
	s_waitcnt lgkmcnt(4)
	v_sub_f32_e32 v8, v63, v8
	s_waitcnt lgkmcnt(3)
	v_sub_f32_e32 v10, v68, v10
	ds_read2st64_b32 v[68:69], v64 offset0:44 offset1:45
	ds_read2st64_b32 v[16:17], v64 offset0:46 offset1:47
	ds_read2st64_b32 v[18:19], v64 offset0:42 offset1:43
	s_waitcnt lgkmcnt(3)
	v_sub_f32_e32 v66, v61, v66
	v_mul_f32_e32 v63, v10, v10
	s_waitcnt lgkmcnt(2)
	v_sub_f32_e32 v68, v60, v68
	ds_read2st64_b32 v[60:61], v64 offset0:48 offset1:49
	ds_read2st64_b32 v[70:71], v64 offset0:52 offset1:53
	ds_read2st64_b32 v[20:21], v64 offset0:54 offset1:55
	ds_read2st64_b32 v[22:23], v64 offset0:50 offset1:51
	ds_read2st64_b32 v[72:73], v64 offset0:56 offset1:57
	v_fmac_f32_e32 v63, v8, v8
	v_fmac_f32_e32 v63, v66, v66
	v_fmac_f32_e32 v63, v68, v68
	s_waitcnt lgkmcnt(4)
	v_sub_f32_e32 v60, v27, v60
	s_waitcnt lgkmcnt(3)
	v_sub_f32_e32 v70, v26, v70
	ds_read2st64_b32 v[74:75], v64 offset0:60 offset1:61
	ds_read2st64_b32 v[24:25], v64 offset0:62 offset1:63
	ds_read2st64_b32 v[26:27], v64 offset0:58 offset1:59
	v_fmac_f32_e32 v63, v60, v60
	v_fmac_f32_e32 v63, v70, v70
	s_waitcnt lgkmcnt(3)
	v_sub_f32_e32 v59, v59, v72
	v_fmac_f32_e32 v63, v59, v59
	s_waitcnt lgkmcnt(2)
	v_sub_f32_e32 v58, v58, v74
	v_fmac_f32_e32 v63, v58, v58
	v_mul_f32_e32 v65, v65, v79
	v_add3_u32 v72, v80, v81, s76
	v_mul_f32_e32 v65, v51, v65
	global_store_short_d16_hi v[6:7], v72, off offset:96
	s_waitcnt lgkmcnt(0)
	s_nop 1
	v_add_f32_dpp v63, v63, v63 quad_perm:[1,0,3,2] row_mask:0xf bank_mask:0xf
	v_bfe_u32 v72, v65, 16, 1
	v_add3_u32 v65, v65, v72, s76
	global_store_short_d16_hi v[6:7], v65, off offset:128
	v_mul_f32_e32 v65, v76, v79
	s_waitcnt lgkmcnt(0)
	s_nop 1
	v_add_f32_dpp v63, v63, v63 quad_perm:[2,3,0,1] row_mask:0xf bank_mask:0xf
	v_mul_f32_e32 v65, v50, v65
	v_bfe_u32 v72, v65, 16, 1
	v_add3_u32 v65, v65, v72, s76
	global_store_short_d16_hi v[6:7], v65, off offset:160
	s_waitcnt lgkmcnt(0)
	s_nop 1
	v_add_f32_dpp v63, v63, v63 row_half_mirror row_mask:0xf bank_mask:0xf
	v_mul_f32_e32 v65, v77, v79
	v_mul_f32_e32 v65, v49, v65
	v_bfe_u32 v72, v65, 16, 1
	v_add3_u32 v65, v65, v72, s76
	s_waitcnt lgkmcnt(0)
; __device__ __forceinline__ unsigned f2bf(float f) { unsigned u = __builtin_bit_cast(unsigned, f); return (u + 0x7fffu + ((u >> 16) & 1u)) >> 16; }
; template <bool SAMPLE> __device__ __forceinline__ void attn_unit16(const Ctx& c, LAS unsigned char* lds, int b, int h, int qb, int wave_s) {
;     ...
;         for (int qt = 0; qt < (SAMPLE ? 1 : 2); ++qt)
; #pragma unroll
;             for (int i = 0; i < 4; ++i) {
;                 float ss = 0.f;
; #pragma unroll
;                 for (int et = 0; et < 8; ++et) { o[qt][et][i] -= X[(g * 64 + qt * 32 + et * 4 + i) * 64 + lane2]; ss += o[qt][et][i] * o[qt][et][i]; }
;                 ss += __shfl_xor(ss, 1); ss += __shfl_xor(ss, 2); ss += __shfl_xor(ss, 4); ss += __shfl_xor(ss, 8);
;                 const float rstd = 1.f / sqrtf(ss * (1.f / 128.f) + 1e-5f);
;                 const int ql = 16 * qt + 4 * q4b + i;
;                 const size_t row = SAMPLE ? (size_t)ROW_S0 + b * 16 + ql : (size_t)b * SEQ + tq0 + ql;
; #pragma unroll
;                 for (int et = 0; et < 8; ++et) Y[row * D + h * 128 + 16 * et + c16b] = (bf16)f2bf(o[qt][et][i] * rstd * sg[et]);
;             }
	s_nop 1
	v_add_f32_dpp v63, v63, v63 row_mirror row_mask:0xf bank_mask:0xf
	v_fmamk_f32 v63, v63, 0x3c000000, v205
	v_mul_f32_e32 v64, 0x4f800000, v63
	v_cmp_gt_f32_e32 vcc, s75, v63
	global_store_short_d16_hi v[6:7], v65, off offset:192
	v_mul_f32_e32 v65, v78, v79
	v_cndmask_b32_e32 v63, v63, v64, vcc
	v_sqrt_f32_e32 v64, v63
	v_mul_f32_e32 v65, v0, v65
	v_sub_f32_e32 v11, v52, v11
	v_sub_f32_e32 v9, v48, v9
	v_add_u32_e32 v72, -1, v64
	v_fma_f32 v74, -v72, v64, v63
	v_cmp_ge_f32_e64 s[0:1], 0, v74
	v_add_u32_e32 v74, 1, v64
	v_mul_f32_e32 v48, v11, v11
	v_cndmask_b32_e64 v72, v64, v72, s[0:1]
	v_fma_f32 v64, -v74, v64, v63
	v_cmp_lt_f32_e64 s[0:1], 0, v64
	v_fmac_f32_e32 v48, v9, v9
	v_sub_f32_e32 v45, v45, v67
	v_cndmask_b32_e64 v64, v72, v74, s[0:1]
	v_mul_f32_e32 v72, 0x37800000, v64
	v_cndmask_b32_e32 v64, v64, v72, vcc
	v_cmp_class_f32_e32 vcc, v63, v206
	v_bfe_u32 v74, v65, 16, 1
	v_add3_u32 v65, v65, v74, s76
	v_cndmask_b32_e32 v63, v64, v63, vcc
	v_div_scale_f32 v64, s[0:1], v63, v63, 1.0
	v_rcp_f32_e32 v72, v64
	global_store_short_d16_hi v[6:7], v65, off offset:224
	v_fmac_f32_e32 v48, v45, v45
	v_sub_f32_e32 v44, v44, v69
	v_fma_f32 v6, -v64, v72, 1.0
	v_fmac_f32_e32 v72, v6, v72
	v_div_scale_f32 v6, vcc, 1.0, v63, 1.0
	v_mul_f32_e32 v7, v6, v72
	v_fma_f32 v65, -v64, v7, v6
	v_fmac_f32_e32 v7, v65, v72
	v_fma_f32 v6, -v64, v7, v6
	v_div_fmas_f32 v6, v6, v72, v7
	v_div_fixup_f32 v63, v6, v63, 1.0
	v_mul_f32_e32 v8, v8, v63
	v_or_b32_e32 v6, 16, v4
	v_mov_b32_e32 v7, s17
	v_mul_f32_e32 v8, v62, v8
	v_lshlrev_b64 v[6:7], 11, v[6:7]
	v_bfe_u32 v64, v8, 16, 1
	v_lshl_add_u64 v[6:7], v[2:3], 0, v[6:7]
	v_add3_u32 v8, v8, v64, s76
	global_store_short_d16_hi v[6:7], v8, off
	v_mul_f32_e32 v8, v10, v63
	v_mul_f32_e32 v8, v55, v8
	v_fmac_f32_e32 v48, v44, v44
	v_sub_f32_e32 v52, v57, v61
	v_bfe_u32 v10, v8, 16, 1
	v_fmac_f32_e32 v48, v52, v52
	v_sub_f32_e32 v56, v56, v71
	v_add3_u32 v8, v8, v10, s76
	v_fmac_f32_e32 v48, v56, v56
	v_sub_f32_e32 v47, v47, v73
	global_store_short_d16_hi v[6:7], v8, off offset:32
	v_mul_f32_e32 v8, v66, v63
	v_fmac_f32_e32 v48, v47, v47
	v_sub_f32_e32 v46, v46, v75
	v_mul_f32_e32 v8, v54, v8
	v_fmac_f32_e32 v48, v46, v46
	v_bfe_u32 v10, v8, 16, 1
	v_add3_u32 v8, v8, v10, s76
	global_store_short_d16_hi v[6:7], v8, off offset:64
	v_mul_f32_e32 v8, v68, v63
	v_mul_f32_e32 v8, v53, v8
	v_bfe_u32 v10, v8, 16, 1
	v_add3_u32 v8, v8, v10, s76
	s_waitcnt lgkmcnt(0)
	s_nop 1
	v_add_f32_dpp v10, v48, v48 quad_perm:[1,0,3,2] row_mask:0xf bank_mask:0xf
	global_store_short_d16_hi v[6:7], v8, off offset:96
	v_mul_f32_e32 v8, v60, v63
	v_mul_f32_e32 v8, v51, v8
	v_bfe_u32 v57, v8, 16, 1
	s_waitcnt lgkmcnt(0)
	s_nop 1
	v_add_f32_dpp v10, v10, v10 quad_perm:[2,3,0,1] row_mask:0xf bank_mask:0xf
	v_add3_u32 v8, v8, v57, s76
	global_store_short_d16_hi v[6:7], v8, off offset:128
	v_mul_f32_e32 v8, v70, v63
	v_mul_f32_e32 v8, v50, v8
	v_bfe_u32 v57, v8, 16, 1
	v_add3_u32 v8, v8, v57, s76
	global_store_short_d16_hi v[6:7], v8, off offset:160
	s_waitcnt lgkmcnt(0)
	s_nop 1
	v_add_f32_dpp v8, v10, v10 row_half_mirror row_mask:0xf bank_mask:0xf
	v_mul_f32_e32 v48, v59, v63
	v_mul_f32_e32 v48, v49, v48
	v_bfe_u32 v57, v48, 16, 1
	v_add3_u32 v48, v48, v57, s76
	s_waitcnt lgkmcnt(0)
	s_nop 1
	v_add_f32_dpp v8, v8, v8 row_mirror row_mask:0xf bank_mask:0xf
	v_fmamk_f32 v8, v8, 0x3c000000, v205
	v_mul_f32_e32 v10, 0x4f800000, v8
	v_cmp_gt_f32_e32 vcc, s75, v8
	global_store_short_d16_hi v[6:7], v48, off offset:192
	v_mul_f32_e32 v48, v58, v63
	v_cndmask_b32_e32 v8, v8, v10, vcc
	v_sqrt_f32_e32 v10, v8
	v_mul_f32_e32 v48, v0, v48
	v_sub_f32_e32 v12, v41, v12
	v_sub_f32_e32 v18, v37, v18
	v_add_u32_e32 v57, -1, v10
	v_fma_f32 v58, -v57, v10, v8
	v_cmp_ge_f32_e64 s[0:1], 0, v58
	v_add_u32_e32 v58, 1, v10
	v_sub_f32_e32 v16, v36, v16
	v_cndmask_b32_e64 v57, v10, v57, s[0:1]
	v_fma_f32 v10, -v58, v10, v8
	v_cmp_lt_f32_e64 s[0:1], 0, v10
	v_sub_f32_e32 v22, v43, v22
	v_sub_f32_e32 v20, v42, v20
	v_cndmask_b32_e64 v10, v57, v58, s[0:1]
	v_mul_f32_e32 v57, 0x37800000, v10
	v_cndmask_b32_e32 v10, v10, v57, vcc
	v_cmp_class_f32_e32 vcc, v8, v206
	v_bfe_u32 v58, v48, 16, 1
	v_add3_u32 v48, v48, v58, s76
	v_cndmask_b32_e32 v8, v10, v8, vcc
	v_div_scale_f32 v10, s[0:1], v8, v8, 1.0
	v_rcp_f32_e32 v57, v10
	global_store_short_d16_hi v[6:7], v48, off offset:224
	v_sub_f32_e32 v26, v39, v26
	v_sub_f32_e32 v24, v38, v24
	v_fma_f32 v6, -v10, v57, 1.0
	v_fmac_f32_e32 v57, v6, v57
	v_div_scale_f32 v6, vcc, 1.0, v8, 1.0
	v_mul_f32_e32 v7, v6, v57
	v_fma_f32 v48, -v10, v7, v6
	v_fmac_f32_e32 v7, v48, v57
	v_fma_f32 v6, -v10, v7, v6
	v_div_fmas_f32 v6, v6, v57, v7
	v_div_fixup_f32 v8, v6, v8, 1.0
	v_mul_f32_e32 v9, v9, v8
	v_or_b32_e32 v6, 17, v4
	v_mov_b32_e32 v7, s17
	v_mul_f32_e32 v9, v62, v9
	v_lshlrev_b64 v[6:7], 11, v[6:7]
	v_bfe_u32 v10, v9, 16, 1
	v_lshl_add_u64 v[6:7], v[2:3], 0, v[6:7]
	v_add3_u32 v9, v9, v10, s76
	global_store_short_d16_hi v[6:7], v9, off
	v_mul_f32_e32 v9, v11, v8
	v_sub_f32_e32 v11, v40, v14
	v_mul_f32_e32 v14, v12, v12
	v_fmac_f32_e32 v14, v11, v11
	v_fmac_f32_e32 v14, v18, v18
	v_mul_f32_e32 v9, v55, v9
	v_fmac_f32_e32 v14, v16, v16
	v_bfe_u32 v10, v9, 16, 1
	v_fmac_f32_e32 v14, v22, v22
	v_add3_u32 v9, v9, v10, s76
	v_fmac_f32_e32 v14, v20, v20
	global_store_short_d16_hi v[6:7], v9, off offset:32
	v_mul_f32_e32 v9, v45, v8
	v_fmac_f32_e32 v14, v26, v26
	v_mul_f32_e32 v9, v54, v9
	v_fmac_f32_e32 v14, v24, v24
	v_bfe_u32 v10, v9, 16, 1
	v_add3_u32 v9, v9, v10, s76
	global_store_short_d16_hi v[6:7], v9, off offset:64
	v_mul_f32_e32 v9, v44, v8
	v_mul_f32_e32 v9, v53, v9
	v_bfe_u32 v10, v9, 16, 1
	v_add3_u32 v9, v9, v10, s76
	s_waitcnt lgkmcnt(0)
; __device__ __forceinline__ unsigned f2bf(float f) { unsigned u = __builtin_bit_cast(unsigned, f); return (u + 0x7fffu + ((u >> 16) & 1u)) >> 16; }
; template <bool SAMPLE> __device__ __forceinline__ void attn_unit16(const Ctx& c, LAS unsigned char* lds, int b, int h, int qb, int wave_s) {
;     ...
;         for (int qt = 0; qt < (SAMPLE ? 1 : 2); ++qt)
; #pragma unroll
;             for (int i = 0; i < 4; ++i) {
;                 float ss = 0.f;
; #pragma unroll
;                 for (int et = 0; et < 8; ++et) { o[qt][et][i] -= X[(g * 64 + qt * 32 + et * 4 + i) * 64 + lane2]; ss += o[qt][et][i] * o[qt][et][i]; }
;                 ss += __shfl_xor(ss, 1); ss += __shfl_xor(ss, 2); ss += __shfl_xor(ss, 4); ss += __shfl_xor(ss, 8);
;                 const float rstd = 1.f / sqrtf(ss * (1.f / 128.f) + 1e-5f);
;                 const int ql = 16 * qt + 4 * q4b + i;
;                 const size_t row = SAMPLE ? (size_t)ROW_S0 + b * 16 + ql : (size_t)b * SEQ + tq0 + ql;
; #pragma unroll
;                 for (int et = 0; et < 8; ++et) Y[row * D + h * 128 + 16 * et + c16b] = (bf16)f2bf(o[qt][et][i] * rstd * sg[et]);
;             }
	s_nop 1
	v_add_f32_dpp v10, v14, v14 quad_perm:[1,0,3,2] row_mask:0xf bank_mask:0xf
	global_store_short_d16_hi v[6:7], v9, off offset:96
	v_mul_f32_e32 v9, v52, v8
	v_mul_f32_e32 v9, v51, v9
	v_bfe_u32 v36, v9, 16, 1
	s_waitcnt lgkmcnt(0)
	s_nop 1
	v_add_f32_dpp v10, v10, v10 quad_perm:[2,3,0,1] row_mask:0xf bank_mask:0xf
	v_add3_u32 v9, v9, v36, s76
	global_store_short_d16_hi v[6:7], v9, off offset:128
	v_mul_f32_e32 v9, v56, v8
	v_mul_f32_e32 v9, v50, v9
	v_bfe_u32 v36, v9, 16, 1
	v_add3_u32 v9, v9, v36, s76
	global_store_short_d16_hi v[6:7], v9, off offset:160
	s_waitcnt lgkmcnt(0)
	s_nop 1
	v_add_f32_dpp v9, v10, v10 row_half_mirror row_mask:0xf bank_mask:0xf
	v_mul_f32_e32 v14, v47, v8
	v_mul_f32_e32 v14, v49, v14
	v_bfe_u32 v36, v14, 16, 1
	v_add3_u32 v14, v14, v36, s76
	s_waitcnt lgkmcnt(0)
	s_nop 1
	v_add_f32_dpp v9, v9, v9 row_mirror row_mask:0xf bank_mask:0xf
	v_fmamk_f32 v9, v9, 0x3c000000, v205
	v_mul_f32_e32 v10, 0x4f800000, v9
	v_cmp_gt_f32_e32 vcc, s75, v9
	global_store_short_d16_hi v[6:7], v14, off offset:192
	v_mul_f32_e32 v8, v46, v8
	v_cndmask_b32_e32 v9, v9, v10, vcc
	v_sqrt_f32_e32 v10, v9
	v_mul_f32_e32 v8, v0, v8
	v_add_u32_e32 v14, -1, v10
	v_fma_f32 v36, -v14, v10, v9
	v_cmp_ge_f32_e64 s[0:1], 0, v36
	v_add_u32_e32 v36, 1, v10
	s_nop 0
	v_cndmask_b32_e64 v14, v10, v14, s[0:1]
	v_fma_f32 v10, -v36, v10, v9
	v_cmp_lt_f32_e64 s[0:1], 0, v10
	s_nop 1
	v_cndmask_b32_e64 v10, v14, v36, s[0:1]
	v_mul_f32_e32 v14, 0x37800000, v10
	v_cndmask_b32_e32 v10, v10, v14, vcc
	v_cmp_class_f32_e32 vcc, v9, v206
	v_bfe_u32 v36, v8, 16, 1
	v_add3_u32 v8, v8, v36, s76
	v_cndmask_b32_e32 v9, v10, v9, vcc
	v_div_scale_f32 v10, s[0:1], v9, v9, 1.0
	v_rcp_f32_e32 v14, v10
	global_store_short_d16_hi v[6:7], v8, off offset:224
	v_fma_f32 v6, -v10, v14, 1.0
	v_fmac_f32_e32 v14, v6, v14
	v_div_scale_f32 v6, vcc, 1.0, v9, 1.0
	v_mul_f32_e32 v7, v6, v14
	v_fma_f32 v8, -v10, v7, v6
	v_fmac_f32_e32 v7, v8, v14
	v_fma_f32 v6, -v10, v7, v6
	v_div_fmas_f32 v6, v6, v14, v7
	v_div_fixup_f32 v8, v6, v9, 1.0
	v_mul_f32_e32 v9, v11, v8
	v_or_b32_e32 v6, 18, v4
	v_mov_b32_e32 v7, s17
	v_mul_f32_e32 v9, v62, v9
	v_lshlrev_b64 v[6:7], 11, v[6:7]
	v_bfe_u32 v10, v9, 16, 1
	v_lshl_add_u64 v[6:7], v[2:3], 0, v[6:7]
	v_add3_u32 v9, v9, v10, s76
	global_store_short_d16_hi v[6:7], v9, off
	v_mul_f32_e32 v9, v12, v8
	v_mul_f32_e32 v9, v55, v9
	v_bfe_u32 v10, v9, 16, 1
	v_add3_u32 v9, v9, v10, s76
	global_store_short_d16_hi v[6:7], v9, off offset:32
	v_mul_f32_e32 v9, v18, v8
	v_sub_f32_e32 v12, v35, v13
	v_mul_f32_e32 v9, v54, v9
	v_sub_f32_e32 v11, v34, v15
	v_mul_f32_e32 v13, v12, v12
	v_bfe_u32 v10, v9, 16, 1
	v_fmac_f32_e32 v13, v11, v11
	v_sub_f32_e32 v14, v33, v19
	v_add3_u32 v9, v9, v10, s76
	v_fmac_f32_e32 v13, v14, v14
	v_sub_f32_e32 v15, v32, v17
	global_store_short_d16_hi v[6:7], v9, off offset:64
	v_mul_f32_e32 v9, v16, v8
	v_fmac_f32_e32 v13, v15, v15
	v_sub_f32_e32 v16, v31, v23
	v_fmac_f32_e32 v13, v16, v16
	v_sub_f32_e32 v17, v30, v21
	v_fmac_f32_e32 v13, v17, v17
	v_sub_f32_e32 v18, v29, v27
	v_fmac_f32_e32 v13, v18, v18
	v_sub_f32_e32 v19, v28, v25
	v_fmac_f32_e32 v13, v19, v19
	v_mul_f32_e32 v9, v53, v9
	v_bfe_u32 v10, v9, 16, 1
	v_add3_u32 v9, v9, v10, s76
	global_store_short_d16_hi v[6:7], v9, off offset:96
	s_waitcnt lgkmcnt(0)
	s_nop 1
	v_add_f32_dpp v10, v13, v13 quad_perm:[1,0,3,2] row_mask:0xf bank_mask:0xf
	v_mul_f32_e32 v9, v22, v8
	v_mul_f32_e32 v9, v51, v9
	v_bfe_u32 v21, v9, 16, 1
	v_add3_u32 v9, v9, v21, s76
	s_waitcnt lgkmcnt(0)
	s_nop 1
	v_add_f32_dpp v10, v10, v10 quad_perm:[2,3,0,1] row_mask:0xf bank_mask:0xf
	global_store_short_d16_hi v[6:7], v9, off offset:128
	v_mul_f32_e32 v9, v20, v8
	v_mul_f32_e32 v9, v50, v9
	v_bfe_u32 v20, v9, 16, 1
	v_add3_u32 v9, v9, v20, s76
	global_store_short_d16_hi v[6:7], v9, off offset:160
	s_waitcnt lgkmcnt(0)
	s_nop 1
	v_add_f32_dpp v9, v10, v10 row_half_mirror row_mask:0xf bank_mask:0xf
	v_mul_f32_e32 v13, v26, v8
	v_mul_f32_e32 v13, v49, v13
	v_bfe_u32 v20, v13, 16, 1
	v_add3_u32 v13, v13, v20, s76
	s_waitcnt lgkmcnt(0)
	s_nop 1
	v_add_f32_dpp v9, v9, v9 row_mirror row_mask:0xf bank_mask:0xf
	v_fmamk_f32 v9, v9, 0x3c000000, v205
	v_mul_f32_e32 v10, 0x4f800000, v9
	v_cmp_gt_f32_e32 vcc, s75, v9
	global_store_short_d16_hi v[6:7], v13, off offset:192
	v_mul_f32_e32 v8, v24, v8
	v_cndmask_b32_e32 v9, v9, v10, vcc
	v_sqrt_f32_e32 v10, v9
	v_mul_f32_e32 v8, v0, v8
	v_or_b32_e32 v4, 19, v4
	v_lshlrev_b64 v[4:5], 11, v[4:5]
	v_add_u32_e32 v13, -1, v10
	v_fma_f32 v20, -v13, v10, v9
	v_cmp_ge_f32_e64 s[0:1], 0, v20
	v_add_u32_e32 v20, 1, v10
	v_lshl_add_u64 v[2:3], v[2:3], 0, v[4:5]
	v_cndmask_b32_e64 v13, v10, v13, s[0:1]
	v_fma_f32 v10, -v20, v10, v9
	v_cmp_lt_f32_e64 s[0:1], 0, v10
	s_nop 1
	v_cndmask_b32_e64 v10, v13, v20, s[0:1]
	v_mul_f32_e32 v13, 0x37800000, v10
	v_cndmask_b32_e32 v10, v10, v13, vcc
	v_cmp_class_f32_e32 vcc, v9, v206
	v_bfe_u32 v20, v8, 16, 1
	v_add3_u32 v8, v8, v20, s76
	v_cndmask_b32_e32 v9, v10, v9, vcc
	v_div_scale_f32 v10, s[0:1], v9, v9, 1.0
	v_rcp_f32_e32 v13, v10
	global_store_short_d16_hi v[6:7], v8, off offset:224
	v_fma_f32 v6, -v10, v13, 1.0
	v_fmac_f32_e32 v13, v6, v13
	v_div_scale_f32 v6, vcc, 1.0, v9, 1.0
	v_mul_f32_e32 v7, v6, v13
	v_fma_f32 v8, -v10, v7, v6
	v_fmac_f32_e32 v7, v8, v13
	v_fma_f32 v6, -v10, v7, v6
	v_div_fmas_f32 v6, v6, v13, v7
	v_div_fixup_f32 v6, v6, v9, 1.0
	v_mul_f32_e32 v4, v11, v6
	v_mul_f32_e32 v4, v62, v4
	v_bfe_u32 v5, v4, 16, 1
	v_add3_u32 v4, v4, v5, s76
	global_store_short_d16_hi v[2:3], v4, off
	v_mul_f32_e32 v4, v12, v6
	v_mul_f32_e32 v4, v55, v4
	v_bfe_u32 v5, v4, 16, 1
	v_add3_u32 v4, v4, v5, s76
	global_store_short_d16_hi v[2:3], v4, off offset:32
	v_mul_f32_e32 v4, v14, v6
	v_mul_f32_e32 v4, v54, v4
	v_bfe_u32 v5, v4, 16, 1
	v_add3_u32 v4, v4, v5, s76
	global_store_short_d16_hi v[2:3], v4, off offset:64
	v_mul_f32_e32 v4, v15, v6
	v_mul_f32_e32 v4, v53, v4
	v_bfe_u32 v5, v4, 16, 1
	v_add3_u32 v4, v4, v5, s76
	global_store_short_d16_hi v[2:3], v4, off offset:96
	v_mul_f32_e32 v4, v16, v6
	v_mul_f32_e32 v4, v51, v4
	v_bfe_u32 v5, v4, 16, 1
	v_add3_u32 v4, v4, v5, s76
	global_store_short_d16_hi v[2:3], v4, off offset:128
	v_mul_f32_e32 v4, v17, v6
	v_mul_f32_e32 v4, v50, v4
	v_bfe_u32 v5, v4, 16, 1
	v_add3_u32 v4, v4, v5, s76
	global_store_short_d16_hi v[2:3], v4, off offset:160
	v_mul_f32_e32 v4, v18, v6
	v_mul_f32_e32 v4, v49, v4
	v_bfe_u32 v5, v4, 16, 1
	v_add3_u32 v4, v4, v5, s76
	global_store_short_d16_hi v[2:3], v4, off offset:192
	v_mul_f32_e32 v4, v19, v6
	v_mul_f32_e32 v0, v0, v4
	v_bfe_u32 v4, v0, 16, 1
	v_add3_u32 v0, v0, v4, s76
	global_store_short_d16_hi v[2:3], v0, off offset:224
